# pk1: stack4 + attention steady loop row-sum chains as packed f32 adds (66 -> 34 VALU adds per 2-step iteration)
# baseline (speedup 1.0000x reference)
.LBB0_413:
	s_mov_b32 s16, s26
	s_mov_b32 s2, s18
	s_mov_b32 s3, s24
	v_lshl_add_u32 v69, s17, 1, v232
	ds_read_b64_tr_b16 v[76:77], v69 offset:24576
	ds_read_b64_tr_b16 v[78:79], v69 offset:25088
	v_pk_add_f32 v[254:255], v[100:101], v[102:103]
	v_pk_add_f32 v[254:255], v[104:105], v[254:255]
	v_cvt_pk_bf16_f32 v160, v100, v101
	v_cvt_pk_bf16_f32 v161, v102, v103
	s_waitcnt lgkmcnt(9)
	v_mfma_f32_32x32x16_bf16 v[132:147], v[208:211], v[176:179], 0
	v_pk_add_f32 v[254:255], v[106:107], v[254:255]
	v_pk_add_f32 v[254:255], v[108:109], v[254:255]
	v_cvt_pk_bf16_f32 v162, v104, v105
	v_cvt_pk_bf16_f32 v163, v106, v107
	s_waitcnt lgkmcnt(8)
	v_mfma_f32_32x32x16_bf16 v[116:131], v[200:203], v[176:179], 0
	ds_read_b64_tr_b16 v[80:81], v69 offset:25600
	ds_read_b64_tr_b16 v[82:83], v69 offset:26112
	v_pk_add_f32 v[254:255], v[110:111], v[254:255]
	v_pk_add_f32 v[254:255], v[112:113], v[254:255]
	v_cvt_pk_bf16_f32 v156, v108, v109
	v_cvt_pk_bf16_f32 v157, v110, v111
	s_waitcnt lgkmcnt(9)
	v_mfma_f32_32x32x16_bf16 v[132:147], v[204:207], v[172:175], v[132:147]
	v_pk_add_f32 v[254:255], v[114:115], v[254:255]
	v_pk_add_f32 v[254:255], v[84:85], v[254:255]
	v_cvt_pk_bf16_f32 v158, v112, v113
	v_cvt_pk_bf16_f32 v159, v114, v115
	s_waitcnt lgkmcnt(8)
	v_mfma_f32_32x32x16_bf16 v[116:131], v[196:199], v[172:175], v[116:131]
	ds_read_b64_tr_b16 v[100:101], v69 offset:26624
	ds_read_b64_tr_b16 v[102:103], v69 offset:27136
	v_pk_add_f32 v[254:255], v[86:87], v[254:255]
	v_pk_add_f32 v[254:255], v[88:89], v[254:255]
	v_cvt_pk_bf16_f32 v152, v84, v85
	v_cvt_pk_bf16_f32 v153, v86, v87
	s_waitcnt lgkmcnt(9)
	v_mfma_f32_32x32x16_bf16 v[132:147], v[192:195], v[168:171], v[132:147]
	v_pk_add_f32 v[254:255], v[90:91], v[254:255]
	v_pk_add_f32 v[254:255], v[92:93], v[254:255]
	v_cvt_pk_bf16_f32 v154, v88, v89
	v_cvt_pk_bf16_f32 v155, v90, v91
	s_waitcnt lgkmcnt(8)
	v_mfma_f32_32x32x16_bf16 v[116:131], v[188:191], v[168:171], v[116:131]
	ds_read_b64_tr_b16 v[84:85], v69 offset:27648
	ds_read_b64_tr_b16 v[86:87], v69 offset:28160
	v_pk_add_f32 v[254:255], v[94:95], v[254:255]
	v_pk_add_f32 v[254:255], v[96:97], v[254:255]
	v_cvt_pk_bf16_f32 v148, v92, v93
	v_cvt_pk_bf16_f32 v149, v94, v95
	s_waitcnt lgkmcnt(9)
	v_mfma_f32_32x32x16_bf16 v[132:147], v[184:187], v[164:167], v[132:147]
	v_pk_add_f32 v[254:255], v[98:99], v[254:255]
	v_add_f32_e32 v72, v254, v255
	v_cvt_pk_bf16_f32 v150, v96, v97
	v_cvt_pk_bf16_f32 v151, v98, v99
	s_waitcnt lgkmcnt(8)
	v_mfma_f32_32x32x16_bf16 v[116:131], v[180:183], v[164:167], v[116:131]
	v_lshl_add_u64 v[74:75], v[0:1], 0, s[14:15]
	v_add_f32_e32 v68, v68, v72
	s_add_i32 m0, s24, s0
	v_lshl_add_u64 v[72:73], v[74:75], 0, s[76:77]
	global_load_lds_dwordx4 v[72:73], off
	s_lshl_b32 s17, s26, 1
	s_add_i32 s17, s17, s1
	s_mov_b32 m0, s17
	v_lshl_add_u64 v[72:73], v[70:71], 0, s[14:15]
	v_lshl_add_u64 v[88:89], v[72:73], 0, s[90:91]
	global_load_lds_dwordx4 v[88:89], off
	s_add_i32 m0, s17, 0x2000
	v_lshl_add_u64 v[88:89], v[72:73], 0, s[92:93]
	global_load_lds_dwordx4 v[88:89], off
	s_waitcnt lgkmcnt(6)
	v_mfma_f32_32x32x16_bf16 v[36:51], v[160:163], v[76:79], v[36:51]
	v_exp_f32_e32 v132, v132
	v_exp_f32_e32 v133, v133
	ds_read_b64_tr_b16 v[76:77], v69 offset:28672
	ds_read_b64_tr_b16 v[78:79], v69 offset:29184
	s_waitcnt lgkmcnt(6)
	v_mfma_f32_32x32x16_bf16 v[36:51], v[156:159], v[80:83], v[36:51]
	v_exp_f32_e32 v134, v134
	v_exp_f32_e32 v135, v135
	ds_read_b64_tr_b16 v[80:81], v69 offset:29696
	ds_read_b64_tr_b16 v[82:83], v69 offset:30208
	s_waitcnt lgkmcnt(6)
	v_mfma_f32_32x32x16_bf16 v[36:51], v[152:155], v[100:103], v[36:51]
	v_exp_f32_e32 v136, v136
	v_exp_f32_e32 v137, v137
	ds_read_b64_tr_b16 v[88:89], v69 offset:30720
	ds_read_b64_tr_b16 v[90:91], v69 offset:31232
	s_waitcnt lgkmcnt(6)
	v_mfma_f32_32x32x16_bf16 v[36:51], v[148:151], v[84:87], v[36:51]
	v_exp_f32_e32 v138, v138
	v_exp_f32_e32 v139, v139
	ds_read_b64_tr_b16 v[84:85], v69 offset:31744
	ds_read_b64_tr_b16 v[86:87], v69 offset:32256
	s_waitcnt lgkmcnt(6)
	v_mfma_f32_32x32x16_bf16 v[52:67], v[160:163], v[76:79], v[52:67]
	v_exp_f32_e32 v140, v140
	v_exp_f32_e32 v141, v141
	ds_read_b64_tr_b16 v[76:77], v69 offset:32768
	ds_read_b64_tr_b16 v[78:79], v69 offset:33280
	s_waitcnt lgkmcnt(6)
	v_mfma_f32_32x32x16_bf16 v[52:67], v[156:159], v[80:83], v[52:67]
	v_exp_f32_e32 v142, v142
	v_exp_f32_e32 v143, v143
	ds_read_b64_tr_b16 v[80:81], v69 offset:33792
	ds_read_b64_tr_b16 v[82:83], v69 offset:34304
	s_waitcnt lgkmcnt(6)
	v_mfma_f32_32x32x16_bf16 v[52:67], v[152:155], v[88:91], v[52:67]
	v_exp_f32_e32 v144, v144
	v_exp_f32_e32 v145, v145
	ds_read_b64_tr_b16 v[88:89], v69 offset:34816
	ds_read_b64_tr_b16 v[90:91], v69 offset:35328
	s_waitcnt lgkmcnt(6)
	v_mfma_f32_32x32x16_bf16 v[52:67], v[148:151], v[84:87], v[52:67]
	v_exp_f32_e32 v146, v146
	v_exp_f32_e32 v147, v147
	ds_read_b64_tr_b16 v[84:85], v69 offset:35840
	ds_read_b64_tr_b16 v[86:87], v69 offset:36352
	s_waitcnt lgkmcnt(6)
	v_mfma_f32_32x32x16_bf16 v[4:19], v[160:163], v[76:79], v[4:19]
	v_exp_f32_e32 v116, v116
	v_exp_f32_e32 v117, v117
	ds_read_b64_tr_b16 v[76:77], v69 offset:36864
	ds_read_b64_tr_b16 v[78:79], v69 offset:37376
	s_waitcnt lgkmcnt(6)
	v_mfma_f32_32x32x16_bf16 v[4:19], v[156:159], v[80:83], v[4:19]
	v_exp_f32_e32 v118, v118
	v_exp_f32_e32 v119, v119
	ds_read_b64_tr_b16 v[80:81], v69 offset:37888
	ds_read_b64_tr_b16 v[82:83], v69 offset:38400
	s_waitcnt lgkmcnt(6)
	v_mfma_f32_32x32x16_bf16 v[4:19], v[152:155], v[88:91], v[4:19]
	v_exp_f32_e32 v120, v120
	v_exp_f32_e32 v121, v121
	ds_read_b64_tr_b16 v[88:89], v69 offset:38912
	ds_read_b64_tr_b16 v[90:91], v69 offset:39424
	s_waitcnt lgkmcnt(6)
	v_mfma_f32_32x32x16_bf16 v[4:19], v[148:151], v[84:87], v[4:19]
	v_exp_f32_e32 v122, v122
	v_exp_f32_e32 v123, v123
	ds_read_b64_tr_b16 v[84:85], v69 offset:39936
	ds_read_b64_tr_b16 v[86:87], v69 offset:40448
	v_add_u32_e32 v69, s16, v230
	ds_read_b128 v[92:95], v69
	ds_read_b128 v[96:99], v69 offset:512
	s_waitcnt lgkmcnt(8)
	v_mfma_f32_32x32x16_bf16 v[20:35], v[160:163], v[76:79], v[20:35]
	v_exp_f32_e32 v124, v124
	v_exp_f32_e32 v125, v125
	ds_read_b128 v[76:79], v69 offset:2048
	ds_read_b128 v[180:183], v69 offset:2560
	s_waitcnt lgkmcnt(8)
	v_mfma_f32_32x32x16_bf16 v[20:35], v[156:159], v[80:83], v[20:35]
	v_exp_f32_e32 v126, v126
	v_exp_f32_e32 v127, v127
	ds_read_b128 v[80:83], v69 offset:4096
	ds_read_b128 v[184:187], v69 offset:4608
	ds_read_b128 v[188:191], v69 offset:6144
	ds_read_b128 v[192:195], v69 offset:6656
	s_waitcnt lgkmcnt(10)
	v_mfma_f32_32x32x16_bf16 v[20:35], v[152:155], v[88:91], v[20:35]
	v_exp_f32_e32 v128, v128
	v_exp_f32_e32 v129, v129
	s_waitcnt lgkmcnt(8)
	v_mfma_f32_32x32x16_bf16 v[20:35], v[148:151], v[84:87], v[20:35]
	v_exp_f32_e32 v130, v130
	v_exp_f32_e32 v131, v131
	s_add_i32 s17, s26, 0x2000
	s_cmpk_lg_i32 s26, 0x4000
	s_cselect_b32 s24, s17, 0
	v_lshl_add_u32 v69, s3, 1, v232
	s_waitcnt vmcnt(3) lgkmcnt(0)
	s_barrier
	ds_read_b64_tr_b16 v[196:197], v69 offset:24576
	ds_read_b64_tr_b16 v[198:199], v69 offset:25088
	s_waitcnt lgkmcnt(9)
	v_mfma_f32_32x32x16_bf16 v[100:115], v[92:95], v[176:179], 0
	v_pk_add_f32 v[248:249], v[132:133], v[134:135]
	v_pk_add_f32 v[248:249], v[136:137], v[248:249]
	v_cvt_pk_bf16_f32 v160, v132, v133
	v_cvt_pk_bf16_f32 v161, v134, v135
	v_pk_add_f32 v[248:249], v[138:139], v[248:249]
	v_pk_add_f32 v[248:249], v[140:141], v[248:249]
	s_waitcnt lgkmcnt(8)
	v_mfma_f32_32x32x16_bf16 v[84:99], v[96:99], v[176:179], 0
	v_cvt_pk_bf16_f32 v162, v136, v137
	v_cvt_pk_bf16_f32 v163, v138, v139
	ds_read_b64_tr_b16 v[132:133], v69 offset:25600
	ds_read_b64_tr_b16 v[134:135], v69 offset:26112
	s_waitcnt lgkmcnt(9)
	v_mfma_f32_32x32x16_bf16 v[100:115], v[76:79], v[172:175], v[100:115]
	v_pk_add_f32 v[248:249], v[142:143], v[248:249]
	v_pk_add_f32 v[248:249], v[144:145], v[248:249]
	v_cvt_pk_bf16_f32 v156, v140, v141
	v_cvt_pk_bf16_f32 v157, v142, v143
	s_waitcnt lgkmcnt(8)
	v_mfma_f32_32x32x16_bf16 v[84:99], v[180:183], v[172:175], v[84:99]
	v_pk_add_f32 v[248:249], v[146:147], v[248:249]
	v_pk_add_f32 v[248:249], v[116:117], v[248:249]
	v_cvt_pk_bf16_f32 v158, v144, v145
	v_cvt_pk_bf16_f32 v159, v146, v147
	ds_read_b64_tr_b16 v[76:77], v69 offset:26624
	ds_read_b64_tr_b16 v[78:79], v69 offset:27136
	s_waitcnt lgkmcnt(9)
	v_mfma_f32_32x32x16_bf16 v[100:115], v[80:83], v[168:171], v[100:115]
	v_pk_add_f32 v[248:249], v[118:119], v[248:249]
	v_pk_add_f32 v[248:249], v[120:121], v[248:249]
	v_cvt_pk_bf16_f32 v152, v116, v117
	v_cvt_pk_bf16_f32 v153, v118, v119
	s_waitcnt lgkmcnt(8)
	v_mfma_f32_32x32x16_bf16 v[84:99], v[184:187], v[168:171], v[84:99]
	v_pk_add_f32 v[248:249], v[122:123], v[248:249]
	v_pk_add_f32 v[248:249], v[124:125], v[248:249]
	v_cvt_pk_bf16_f32 v154, v120, v121
	v_cvt_pk_bf16_f32 v155, v122, v123
	ds_read_b64_tr_b16 v[80:81], v69 offset:27648
	ds_read_b64_tr_b16 v[82:83], v69 offset:28160
	s_waitcnt lgkmcnt(9)
	v_mfma_f32_32x32x16_bf16 v[100:115], v[188:191], v[164:167], v[100:115]
	v_pk_add_f32 v[248:249], v[126:127], v[248:249]
	v_pk_add_f32 v[248:249], v[128:129], v[248:249]
	v_cvt_pk_bf16_f32 v148, v124, v125
	v_cvt_pk_bf16_f32 v149, v126, v127
	s_waitcnt lgkmcnt(8)
	v_mfma_f32_32x32x16_bf16 v[84:99], v[192:195], v[164:167], v[84:99]
	v_pk_add_f32 v[248:249], v[130:131], v[248:249]
	v_add_f32_e32 v116, v248, v249
	v_cvt_pk_bf16_f32 v150, v128, v129
	v_cvt_pk_bf16_f32 v151, v130, v131
	s_add_i32 m0, s26, s0
	v_lshl_add_u64 v[74:75], v[74:75], 0, s[28:29]
	global_load_lds_dwordx4 v[74:75], off
	s_lshl_b32 s3, s24, 1
	s_add_i32 s3, s3, s1
	s_mov_b32 m0, s3
	v_lshl_add_u64 v[74:75], v[72:73], 0, s[66:67]
	global_load_lds_dwordx4 v[74:75], off
	s_add_i32 m0, s3, 0x2000
	v_lshl_add_u64 v[72:73], v[72:73], 0, s[72:73]
	global_load_lds_dwordx4 v[72:73], off
	v_add_f32_e32 v68, v68, v116
	s_waitcnt lgkmcnt(6)
	v_mfma_f32_32x32x16_bf16 v[36:51], v[160:163], v[196:199], v[36:51]
	v_exp_f32_e32 v100, v100
	v_exp_f32_e32 v101, v101
	ds_read_b64_tr_b16 v[72:73], v69 offset:28672
	ds_read_b64_tr_b16 v[74:75], v69 offset:29184
	s_waitcnt lgkmcnt(6)
	v_mfma_f32_32x32x16_bf16 v[36:51], v[156:159], v[132:135], v[36:51]
	v_exp_f32_e32 v102, v102
	v_exp_f32_e32 v103, v103
	ds_read_b64_tr_b16 v[116:117], v69 offset:29696
	ds_read_b64_tr_b16 v[118:119], v69 offset:30208
	s_waitcnt lgkmcnt(6)
	v_mfma_f32_32x32x16_bf16 v[36:51], v[152:155], v[76:79], v[36:51]
	v_exp_f32_e32 v104, v104
	v_exp_f32_e32 v105, v105
	ds_read_b64_tr_b16 v[76:77], v69 offset:30720
	ds_read_b64_tr_b16 v[78:79], v69 offset:31232
	s_waitcnt lgkmcnt(6)
	v_mfma_f32_32x32x16_bf16 v[36:51], v[148:151], v[80:83], v[36:51]
	v_exp_f32_e32 v106, v106
	v_exp_f32_e32 v107, v107
	ds_read_b64_tr_b16 v[80:81], v69 offset:31744
	ds_read_b64_tr_b16 v[82:83], v69 offset:32256
	s_waitcnt lgkmcnt(6)
	v_mfma_f32_32x32x16_bf16 v[52:67], v[160:163], v[72:75], v[52:67]
	v_exp_f32_e32 v108, v108
	v_exp_f32_e32 v109, v109
	ds_read_b64_tr_b16 v[72:73], v69 offset:32768
	ds_read_b64_tr_b16 v[74:75], v69 offset:33280
	s_waitcnt lgkmcnt(6)
	v_mfma_f32_32x32x16_bf16 v[52:67], v[156:159], v[116:119], v[52:67]
	v_exp_f32_e32 v110, v110
	v_exp_f32_e32 v111, v111
	ds_read_b64_tr_b16 v[116:117], v69 offset:33792
	ds_read_b64_tr_b16 v[118:119], v69 offset:34304
	s_waitcnt lgkmcnt(6)
	v_mfma_f32_32x32x16_bf16 v[52:67], v[152:155], v[76:79], v[52:67]
	v_exp_f32_e32 v112, v112
	v_exp_f32_e32 v113, v113
	ds_read_b64_tr_b16 v[76:77], v69 offset:34816
	ds_read_b64_tr_b16 v[78:79], v69 offset:35328
	s_waitcnt lgkmcnt(6)
	v_mfma_f32_32x32x16_bf16 v[52:67], v[148:151], v[80:83], v[52:67]
	v_exp_f32_e32 v114, v114
	v_exp_f32_e32 v115, v115
	ds_read_b64_tr_b16 v[80:81], v69 offset:35840
	ds_read_b64_tr_b16 v[82:83], v69 offset:36352
	s_waitcnt lgkmcnt(6)
	v_mfma_f32_32x32x16_bf16 v[4:19], v[160:163], v[72:75], v[4:19]
	v_exp_f32_e32 v84, v84
	v_exp_f32_e32 v85, v85
	ds_read_b64_tr_b16 v[72:73], v69 offset:36864
	ds_read_b64_tr_b16 v[74:75], v69 offset:37376
	s_waitcnt lgkmcnt(6)
	v_mfma_f32_32x32x16_bf16 v[4:19], v[156:159], v[116:119], v[4:19]
	v_exp_f32_e32 v86, v86
	v_exp_f32_e32 v87, v87
	ds_read_b64_tr_b16 v[116:117], v69 offset:37888
	ds_read_b64_tr_b16 v[118:119], v69 offset:38400
	s_waitcnt lgkmcnt(6)
	v_mfma_f32_32x32x16_bf16 v[4:19], v[152:155], v[76:79], v[4:19]
	v_exp_f32_e32 v88, v88
	v_exp_f32_e32 v89, v89
	ds_read_b64_tr_b16 v[76:77], v69 offset:38912
	ds_read_b64_tr_b16 v[78:79], v69 offset:39424
	s_waitcnt lgkmcnt(6)
	v_mfma_f32_32x32x16_bf16 v[4:19], v[148:151], v[80:83], v[4:19]
	v_exp_f32_e32 v90, v90
	v_exp_f32_e32 v91, v91
	ds_read_b64_tr_b16 v[80:81], v69 offset:39936
	ds_read_b64_tr_b16 v[82:83], v69 offset:40448
	v_add_u32_e32 v69, s24, v230
	ds_read_b128 v[208:211], v69
	ds_read_b128 v[200:203], v69 offset:512
	s_waitcnt lgkmcnt(8)
	v_mfma_f32_32x32x16_bf16 v[20:35], v[160:163], v[72:75], v[20:35]
	v_exp_f32_e32 v92, v92
	v_exp_f32_e32 v93, v93
	ds_read_b128 v[204:207], v69 offset:2048
	ds_read_b128 v[196:199], v69 offset:2560
	s_waitcnt lgkmcnt(8)
	v_mfma_f32_32x32x16_bf16 v[20:35], v[156:159], v[116:119], v[20:35]
	v_exp_f32_e32 v94, v94
	v_exp_f32_e32 v95, v95
	ds_read_b128 v[192:195], v69 offset:4096
	ds_read_b128 v[188:191], v69 offset:4608
	ds_read_b128 v[184:187], v69 offset:6144
	ds_read_b128 v[180:183], v69 offset:6656
	s_waitcnt lgkmcnt(10)
	v_mfma_f32_32x32x16_bf16 v[20:35], v[152:155], v[76:79], v[20:35]
	v_exp_f32_e32 v96, v96
	v_exp_f32_e32 v97, v97
	s_waitcnt lgkmcnt(8)
	v_mfma_f32_32x32x16_bf16 v[20:35], v[148:151], v[80:83], v[20:35]
	v_exp_f32_e32 v98, v98
	v_exp_f32_e32 v99, v99
	s_add_i32 s3, s24, 0x2000
	s_cmpk_lg_i32 s24, 0x4000
	s_cselect_b32 s26, s3, 0
	s_add_i32 s18, s2, 2
	s_add_u32 s14, s14, 0x20000
	s_addc_u32 s15, s15, 0
	s_mov_b32 s17, s16
	s_cmp_ge_u32 s18, s21
	s_waitcnt vmcnt(3) lgkmcnt(0)
	s_barrier
	s_cbranch_scc0 .LBB0_413
	s_add_i32 s64, s2, -3
	s_lshl_b64 s[12:13], s[12:13], 9
	s_add_i32 s2, s64, 1
	s_cmp_lt_u32 s2, s21
	s_cbranch_scc0 .LBB0_441
